# GQA bias: the packed add of +0.0 to each LUT value (nm_ term, zero in the non-frozen path) removed in prologue and loop (31 v_pk_add_f32 + nops); downstream values identical
# baseline (speedup 1.0000x reference)
; template <int MODE, bool FROZEN = false>
; __device__ __forceinline__ bool attn_unit(LAS unsigned char* lds, const Params& p, int l, int ua, int ub) {
;     ...
;         const int g = ua, qb = ub, hq = g * 4 + (wid >> 1); qtok0 = qb * 64 + (wid & 1) * 32; lut_sel = wid >> 1;
;         qcol = 3072 + hq * 64; kcol = 3584 + g * 64; vcol = 1024 + g * 64; ocol = hq * 64;
;         const int tlo = max(qb - 2, 0), thi = min(qb + 2, S / 64 - 1); kt0 = tlo * 64; NT = thi - tlo + 1; wt_hi = NT;
;         for (int i = tid; i < 4 * 449; i += 512) { const int hh = i / 449, rel = i % 449 - 224; lut[i] = (rel >= -128 && rel <= 128) ? p.rel_bias[t5_bucket(rel) * 12 + 4 + g * 4 + hh] * LOG2E : NEGBIG; }
;         m_run = p.gqa_sink[l * 8 + hq] * LOG2E; l_run = (hi == 0) ? 1.0f : 0.0f;
;     }
;     bf16x8 qf[4];
;     { const bf16_t* qp = proj + (size_t)(qtok0 + r32) * NPROJ + qcol + 8 * hi;
; #pragma unroll
;       for (int d0 = 0; d0 < 4; ++d0) qf[d0] = *(const bf16x8*)(qp + 16 * d0); }
;     f32x16 o[NB];
; #pragma unroll
;     for (int nb = 0; nb < NB; ++nb)
; #pragma unroll
;         for (int r = 0; r < 16; ++r) o[nb][r] = 0.f;
;     u32x4 kr[NKC], vr[NVC];
;     unsigned ksrc[NKC], vsrc[NVC]; int kdst[NKC], vdst[NVC];
;     const bf16_t* kvbase = proj + (size_t)kt0 * NPROJ;
; #pragma unroll
;     for (int i = 0; i < NKC; ++i) { const int cid = tid + 512 * i, row = cid / KCH, ch = cid % KCH; ksrc[i] = (unsigned)(row * NPROJ + kcol + ch * 8); kdst[i] = OFF_K + row * KPB + ch * 16; }
; #pragma unroll
;     for (int i = 0; i < NVC; ++i) { const int cid = tid + 512 * i, row = cid >> 3, ch = cid & 7; vsrc[i] = (unsigned)((vcol + row) * S + ch * 8); vdst[i] = OFF_V + row * VTP + (ch >> 1) * 32 + (ch & 1) * 8; }
;     const bf16_t* vtbase = vtg + kt0;
;     {
;         u32x4 k1[NKC];
; #pragma unroll
;         for (int i = 0; i < NKC; ++i) { kr[i] = *(const u32x4*)(kvbase + ksrc[i]); k1[i] = *(const u32x4*)(kvbase + (size_t)64 * NPROJ + ksrc[i]); }
; #pragma unroll
;         for (int i = 0; i < NVC; ++i) vr[i] = *(const u32x4*)(vtbase + vsrc[i]);
; #pragma unroll
;         for (int i = 0; i < NKC; ++i) { *(LAS u32x4*)(lds + kdst[i]) = kr[i]; *(LAS u32x4*)(lds + kdst[i] + KBUF) = k1[i]; }
; #pragma unroll
;         for (int i = 0; i < NVC; ++i) { *(LAS u32x2*)(lds + vdst[i]) = (u32x2){vr[i].x, vr[i].y}; *(LAS u32x2*)(lds + vdst[i] + 16) = (u32x2){vr[i].z, vr[i].w}; }
; #pragma unroll
.LBB0_503:
	s_or_b64 exec, exec, s[0:1]
	s_ashr_i32 s10, s20, 1
	s_lshr_b32 s4, s21, 1
	s_lshl_b32 s1, s10, 6
	s_and_b32 s4, s4, 32
	s_max_i32 s11, s10, 2
	s_ashr_i32 s12, s21, 7
	s_or_b32 s5, s4, s1
	s_lshl_b32 s1, s11, 6
	s_add_i32 s0, s12, s8
	s_add_i32 s8, s1, 0xffffff80
	v_readlane_b32 s1, v255, 13
	s_lshl_b32 s4, s0, 6
	s_add_i32 s0, s0, s1
	s_min_i32 s13, s10, 0xfd
	s_ashr_i32 s1, s0, 31
	v_readlane_b32 s40, v254, 57
	s_lshl_b32 s14, s22, 6
	s_sub_i32 s13, s13, s11
	s_lshl_b64 s[0:1], s[0:1], 2
	v_readlane_b32 s52, v255, 5
	v_readlane_b32 s53, v255, 6
	s_add_u32 s0, s52, s0
	v_and_b32_e32 v92, 31, v2
	s_addc_u32 s1, s53, s1
	global_load_dword v36, v197, s[0:1]
	v_or_b32_e32 v32, s5, v92
	v_mov_b64_e32 v[0:1], s[34:35]
	s_movk_i32 s0, 0x1e00
	v_bfe_u32 v35, v2, 5, 1
	v_mad_i64_i32 v[0:1], s[0:1], v32, s0, v[0:1]
	s_ashr_i32 s5, s4, 31
	v_lshl_add_u64 v[0:1], s[4:5], 1, v[0:1]
	v_lshlrev_b32_e32 v196, 4, v35
	v_lshl_add_u64 v[0:1], v[0:1], 0, v[196:197]
	s_mov_b64 s[0:1], 0x1800
	v_lshl_add_u64 v[4:5], v[0:1], 0, s[0:1]
	s_movk_i32 s0, 0x1000
	v_add_co_u32_e64 v0, s[0:1], s0, v0
	s_movk_i32 s15, 0xf00
	s_nop 0
	v_addc_co_u32_e64 v1, s[0:1], 0, v1, s[0:1]
	global_load_dwordx4 v[68:71], v[0:1], off offset:2048
	global_load_dwordx4 v[72:75], v[4:5], off offset:32
	global_load_dwordx4 v[76:79], v[4:5], off offset:64
	global_load_dwordx4 v[80:83], v[4:5], off offset:96
	v_ashrrev_i32_e32 v0, 31, v2
	v_lshrrev_b32_e32 v0, 29, v0
	v_add_u32_e32 v0, v2, v0
	v_ashrrev_i32_e32 v1, 3, v0
	v_and_b32_e32 v0, -8, v0
	v_sub_u32_e32 v3, v2, v0
	v_mul_lo_u32 v0, v1, s15
	s_movk_i32 s16, 0x90
	v_or_b32_e32 v0, s14, v0
	v_lshlrev_b32_e32 v4, 3, v3
	s_movk_i32 s15, 0xe00
	v_mul_lo_u32 v12, v1, s16
	v_ashrrev_i32_e32 v1, 3, v2
	s_mul_i32 s0, s8, 0x1e00
	v_add3_u32 v0, v0, v4, s15
	v_add_u32_e32 v4, s14, v1
	v_mul_lo_u32 v14, v1, s16
	v_lshlrev_b32_e32 v1, 4, v2
	s_mul_hi_u32 s1, s8, 0x1e00
	s_add_u32 s0, s34, s0
	v_and_b32_e32 v15, 0x60, v1
	v_lshlrev_b32_e32 v1, 3, v2
	s_addc_u32 s1, s35, s1
	v_lshlrev_b32_e32 v13, 4, v3
	v_and_b32_e32 v3, 7, v2
	v_lshlrev_b32_e32 v16, 4, v2
	v_and_b32_e32 v16, 16, v16
	v_mov_b32_e32 v1, v197
	v_lshlrev_b32_e32 v3, 3, v3
	v_lshl_add_u64 v[108:109], v[0:1], 1, s[0:1]
	s_mov_b32 s0, 0x78000
	v_lshl_or_b32 v3, v4, 14, v3
	s_lshl_b64 s[14:15], s[8:9], 1
	v_add_co_u32_e64 v4, s[0:1], s0, v108
	v_add_u32_e32 v8, 0x1000000, v3
	s_add_u32 s14, s6, s14
	global_load_dwordx4 v[0:3], v[108:109], off
	v_addc_co_u32_e64 v5, s[0:1], 0, v109, s[0:1]
	s_addc_u32 s15, s7, s15
	global_load_dwordx4 v[4:7], v[4:5], off
	v_mov_b32_e32 v9, v197
	v_lshl_add_u64 v[110:111], v[8:9], 1, s[14:15]
	global_load_dwordx4 v[8:11], v[110:111], off
	v_add3_u32 v33, 0, v12, v13
	s_mov_b32 s0, 0xf0000
	v_add_u32_e32 v37, 0, v196
	v_mad_u32_u24 v145, v92, s16, v37
	v_cmp_eq_u32_e32 vcc, 0, v35
	v_readlane_b32 s41, v254, 58
	v_readlane_b32 s42, v254, 59
	v_readlane_b32 s43, v254, 60
	v_readlane_b32 s44, v254, 61
	v_readlane_b32 s45, v254, 62
	v_readlane_b32 s46, v254, 63
	v_readlane_b32 s47, v255, 0
	v_readlane_b32 s48, v255, 1
	v_readlane_b32 s49, v255, 2
	v_readlane_b32 s50, v255, 3
	v_readlane_b32 s51, v255, 4
	s_waitcnt vmcnt(7)
	v_mul_f32_e32 v93, 0x3fb8aa3b, v36
	v_readlane_b32 s54, v255, 7
	v_readlane_b32 s55, v255, 8
	s_waitcnt vmcnt(2)
	ds_write_b128 v33, v[0:3]
	s_waitcnt vmcnt(1)
	ds_write_b128 v33, v[4:7] offset:9216
	v_add_u32_e32 v0, 0, v14
	v_add3_u32 v144, v0, v16, v15
	v_add_u32_e32 v0, 0x4800, v144
	s_waitcnt vmcnt(0)
	ds_write_b128 v0, v[8:11]
	v_add_co_u32_e64 v0, s[0:1], s0, v108
	s_nop 1
	v_addc_co_u32_e64 v1, s[0:1], 0, v109, s[0:1]
	global_load_dwordx4 v[88:91], v[0:1], off
	global_load_dwordx4 v[84:87], v[110:111], off offset:128
	s_waitcnt lgkmcnt(0)
	s_barrier
; #define ATT_MAX3(dst) do { float tm_ = max3f(sB0[0], sB1[0], sB0[1]), tn_ = max3f(sB1[1], sB0[2], sB1[2]); \
;         _Pragma("unroll") for (int r = 3; r < 15; r += 2) { tm_ = max3f(tm_, sB0[r], sB1[r]); tn_ = max3f(tn_, sB0[r + 1], sB1[r + 1]); } \
;         tm_ = max3f(tm_, sB0[15], sB1[15]); dst = max3f(tm_, tn_, tn_); } while (0)
; template <int MODE, bool FROZEN = false>
; __device__ __forceinline__ bool attn_unit(LAS unsigned char* lds, const Params& p, int l, int ua, int ub) {
;     ...
;     const int qpos = qtok0 + r32;
;     const int i16 = lane & 15, q4 = i16 >> 2, p4 = i16 & 3, blk = (lane >> 4) & 1;
;     const int vlane_off = r32 * VTP + hi * 16;
;     const int klane_off = r32 * KPB + (kfo + 8 * hi) * 2;
;     f32x16 sB0, sB1; float cbB = 0.f; bool fastB = false;
;     ...
;     float cb_pos = 0.f, cb_neg = 0.f;
;     if constexpr (MODE == 1) { cb_pos = lut[448]; cb_neg = lut[0]; }
;     ATT_QK(0);
;     if constexpr (FROZEN) m_run = cb_neg;
;     { float tm0 = 0.f; if constexpr (!FROZEN) ATT_MAX3(tm0); ATT_BIAS(0, tm0); ATT_UPD(tm0); }
;     __syncthreads();
;     for (int t = 0; t < NT; ++t) {
	ds_read_b128 v[0:3], v145 offset:4608
	ds_read_b128 v[4:7], v145
	ds_read_b128 v[38:41], v145 offset:32
	s_waitcnt lgkmcnt(1)
	v_mfma_f32_32x32x16_bf16 v[16:31], v[4:7], v[68:71], 0
	ds_read_b128 v[42:45], v145 offset:4640
	s_mul_i32 s0, s12, 0x704
	v_mfma_f32_32x32x16_bf16 v[0:15], v[0:3], v[68:71], 0
	s_waitcnt lgkmcnt(1)
	v_mfma_f32_32x32x16_bf16 v[16:31], v[38:41], v[72:75], v[16:31]
	s_waitcnt lgkmcnt(0)
	v_mfma_f32_32x32x16_bf16 v[0:15], v[42:45], v[72:75], v[0:15]
	ds_read_b128 v[38:41], v145 offset:64
	ds_read_b128 v[42:45], v145 offset:4672
	s_waitcnt lgkmcnt(1)
	v_mfma_f32_32x32x16_bf16 v[16:31], v[38:41], v[76:79], v[16:31]
	s_waitcnt lgkmcnt(0)
	v_mfma_f32_32x32x16_bf16 v[0:15], v[42:45], v[76:79], v[0:15]
	ds_read_b128 v[38:41], v145 offset:96
	ds_read_b128 v[42:45], v145 offset:4704
	s_waitcnt lgkmcnt(1)
	v_mfma_f32_32x32x16_bf16 v[16:31], v[38:41], v[80:83], v[16:31]
	v_sub_u32_e32 v38, s8, v32
	v_lshlrev_b32_e32 v38, 2, v38
	v_add3_u32 v37, v37, v38, s0
	v_add_u32_e32 v38, 0x9380, v37
	ds_read2_b32 v[38:39], v38 offset1:1
	s_waitcnt lgkmcnt(0)
	s_nop 4
	v_pk_add_f32 v[16:17], v[16:17], v[38:39]
	v_add_u32_e32 v38, 0x9388, v37
	ds_read2_b32 v[38:39], v38 offset1:1
	v_mfma_f32_32x32x16_bf16 v[0:15], v[42:45], v[80:83], v[0:15]
	s_waitcnt lgkmcnt(0)
	v_add_f32_e64 v38, v38, 0
	v_add_f32_e64 v39, v39, 0
	v_add_f32_e64 v18, v18, v38
	v_add_f32_e64 v19, v19, v39
	v_add_u32_e32 v38, 0x93a0, v37
	ds_read2_b32 v[38:39], v38 offset1:1
	s_waitcnt lgkmcnt(0)
	v_pk_add_f32 v[20:21], v[20:21], v[38:39]
	v_add_u32_e32 v38, 0x93a8, v37
	ds_read2_b32 v[38:39], v38 offset1:1
	s_waitcnt lgkmcnt(0)
	v_pk_add_f32 v[22:23], v[22:23], v[38:39]
	v_add_u32_e32 v38, 0x93c0, v37
	ds_read2_b32 v[38:39], v38 offset1:1
	s_waitcnt lgkmcnt(0)
	v_pk_add_f32 v[24:25], v[24:25], v[38:39]
	v_add_u32_e32 v38, 0x93c8, v37
	ds_read2_b32 v[38:39], v38 offset1:1
	s_waitcnt lgkmcnt(0)
	v_pk_add_f32 v[26:27], v[26:27], v[38:39]
	v_add_u32_e32 v38, 0x93e0, v37
	ds_read2_b32 v[38:39], v38 offset1:1
	s_waitcnt lgkmcnt(0)
	v_pk_add_f32 v[28:29], v[28:29], v[38:39]
	v_add_u32_e32 v38, 0x93e8, v37
	ds_read2_b32 v[38:39], v38 offset1:1
	s_waitcnt lgkmcnt(0)
	v_pk_add_f32 v[30:31], v[30:31], v[38:39]
	v_add_u32_e32 v38, 0x9400, v37
	ds_read2_b32 v[38:39], v38 offset1:1
	s_waitcnt lgkmcnt(0)
	v_pk_add_f32 v[0:1], v[0:1], v[38:39]
	v_add_u32_e32 v38, 0x9408, v37
	ds_read2_b32 v[38:39], v38 offset1:1
	s_waitcnt lgkmcnt(0)
	v_pk_add_f32 v[2:3], v[2:3], v[38:39]
	v_add_u32_e32 v38, 0x9420, v37
	ds_read2_b32 v[38:39], v38 offset1:1
	s_waitcnt lgkmcnt(0)
	v_pk_add_f32 v[4:5], v[4:5], v[38:39]
	v_add_u32_e32 v38, 0x9428, v37
	ds_read2_b32 v[38:39], v38 offset1:1
	s_waitcnt lgkmcnt(0)
	v_pk_add_f32 v[6:7], v[6:7], v[38:39]
	v_add_u32_e32 v38, 0x9440, v37
	ds_read2_b32 v[38:39], v38 offset1:1
	s_waitcnt lgkmcnt(0)
	v_pk_add_f32 v[8:9], v[8:9], v[38:39]
	v_add_u32_e32 v38, 0x9448, v37
	ds_read2_b32 v[38:39], v38 offset1:1
	s_waitcnt lgkmcnt(0)
	v_pk_add_f32 v[10:11], v[10:11], v[38:39]
	v_add_u32_e32 v38, 0x9460, v37
	ds_read2_b32 v[38:39], v38 offset1:1
	v_add_u32_e32 v37, 0x9468, v37
	s_waitcnt lgkmcnt(0)
	v_pk_add_f32 v[12:13], v[12:13], v[38:39]
	ds_read2_b32 v[38:39], v37 offset1:1
	s_waitcnt lgkmcnt(0)
	v_pk_add_f32 v[14:15], v[14:15], v[38:39]
	v_max_f32_e32 v37, v16, v0
	v_max3_f32 v38, v1, v18, v2
	v_max3_f32 v37, v37, v17, v19
	v_max3_f32 v38, v38, v20, v4
	v_max3_f32 v37, v37, v3, v21
	v_max3_f32 v38, v38, v22, v6
	v_max3_f32 v37, v37, v5, v23
	v_max3_f32 v38, v38, v24, v8
	v_max3_f32 v37, v37, v7, v25
	v_max3_f32 v38, v38, v26, v10
	v_max3_f32 v37, v37, v9, v27
	v_max3_f32 v38, v38, v28, v12
	v_max3_f32 v37, v37, v11, v29
	v_max3_f32 v38, v38, v30, v14
	v_max3_f32 v37, v37, v13, v31
	v_max3_f32 v37, v37, v15, v38
	v_mov_b32_e32 v38, v37
	s_nop 1
	v_permlane32_swap_b32_e32 v37, v38
	v_max_f32_e32 v38, v38, v38
	v_max_f32_e32 v37, v37, v37
	v_max_f32_e32 v37, v37, v38
	v_add_f32_e32 v38, 0, v37
	v_max_f32_e32 v94, v93, v38
	s_mov_b32 s8, 0x3fb8aa3b
	v_fma_f32 v36, v36, s8, -v94
	v_exp_f32_e32 v95, v36
	v_cndmask_b32_e64 v96, 0, 1.0, vcc
	v_cmp_gt_f32_e32 vcc, v37, v93
	s_cmp_eq_u64 vcc, 0
	v_mul_f32_e32 v36, 0, v95
	s_cselect_b64 vcc, -1, 0
	v_cndmask_b32_e64 v52, v36, 0, vcc
	v_cndmask_b32_e64 v95, v95, 1.0, vcc
	v_mov_b32_e32 v53, v52
	v_mov_b32_e32 v54, v52
	v_mov_b32_e32 v55, v52
	v_mov_b32_e32 v56, v52
	v_mov_b32_e32 v57, v52
	v_mov_b32_e32 v58, v52
	v_mov_b32_e32 v59, v52
	v_mov_b32_e32 v60, v52
	v_mov_b32_e32 v61, v52
	v_mov_b32_e32 v62, v52
	v_mov_b32_e32 v63, v52
	v_mov_b32_e32 v64, v52
	v_mov_b32_e32 v65, v52
	v_mov_b32_e32 v66, v52
	v_mov_b32_e32 v67, v52
	v_mov_b32_e32 v36, v52
	v_mov_b32_e32 v37, v52
	v_mov_b32_e32 v38, v52
	v_mov_b32_e32 v39, v52
	v_mov_b32_e32 v40, v52
	v_mov_b32_e32 v41, v52
	v_mov_b32_e32 v42, v52
	v_mov_b32_e32 v43, v52
	v_mov_b32_e32 v44, v52
	v_mov_b32_e32 v45, v52
	v_mov_b32_e32 v46, v52
	v_mov_b32_e32 v47, v52
	v_mov_b32_e32 v48, v52
	v_mov_b32_e32 v49, v52
	v_mov_b32_e32 v50, v52
	v_mov_b32_e32 v51, v52
	v_mul_f32_e32 v146, v96, v95
	s_cmp_gt_i32 s13, -5
	s_barrier
	s_cbranch_scc0 .LBB0_489
	s_lshl_b32 s1, s11, 8
	s_add_i32 s0, s0, s1
	v_mul_u32_u24_e32 v95, 0x90, v92
	v_cndmask_b32_e32 v149, v94, v93, vcc
	v_add_u32_e32 v93, s0, v196
	v_lshlrev_b32_e32 v92, 2, v92
	s_lshl_b32 s0, s21, 1
	v_sub_u32_e32 v92, v93, v92
	s_and_b32 s0, s0, 0x80
	v_subrev_u32_e32 v92, s0, v92
	s_lshl_b32 s0, s10, 8
	v_subrev_u32_e32 v92, s0, v92
	v_readlane_b32 s0, v254, 49
	v_add3_u32 v147, 0, v95, v196
	s_add_i32 s12, s13, 4
	s_add_i32 s13, s13, 5
	v_add_u32_e32 v148, s0, v92
	s_mov_b32 s15, 0
	s_add_i32 s8, s15, 2
	s_cmp_gt_i32 s8, s12
	s_cbranch_scc1 .LBB0_506

; template <int MODE, bool FROZEN = false>
; __device__ __forceinline__ bool attn_unit(LAS unsigned char* lds, const Params& p, int l, int ua, int ub) {
;     ...
;     for (int t = 0; t < NT; ++t) {
;         if (t + 2 < NT) {
; #pragma unroll
;             for (int i = 0; i < NKC; ++i) *(LAS u32x4*)(lds + kdst[i] + (t & 1) * KBUF) = kr[i];
;         }
;         if (t + 1 < NT) {
; #pragma unroll
;             for (int i = 0; i < NVC; ++i) { *(LAS u32x2*)(lds + vdst[i] + ((t + 1) & 1) * VBUF) = (u32x2){vr[i].x, vr[i].y}; *(LAS u32x2*)(lds + vdst[i] + ((t + 1) & 1) * VBUF + 16) = (u32x2){vr[i].z, vr[i].w}; }
;         }
;         {
;             const size_t advk = (size_t)min(t + 3, NT - 1) * 64 * NPROJ, advv = (size_t)min(t + 2, NT - 1) * 64;
; #pragma unroll
;             for (int i = 0; i < NKC; ++i) kr[i] = *(const u32x4*)(kvbase + advk + ksrc[i]);
; #pragma unroll
;             for (int i = 0; i < NVC; ++i) vr[i] = *(const u32x4*)(vtbase + advv + vsrc[i]);
;         }
;         f32x16 sA0 = sB0, sA1 = sB1;
;         const float c2 = cbB - m_run;
;         const LAS unsigned char* Vb = lds + OFF_V + (t & 1) * VBUF + vlane_off;
;         const LAS unsigned char* Kb = lds + OFF_K + ((t + 1) & 1) * KBUF + klane_off;
;     ...
;         bf16x8 kf0[4], kf1[4], va[NB], vb[NB], pf0, pf1; float ps0, ps1, ps2, ps3;
;         VLOAD(0, va);
;         EXPCVT(0, pf0, ps0);
;         SBAR_();
;         VLOAD(1, vb); PVMMA(va, pf0); EXPCVT(1, pf1, ps1); _Pragma("unroll") for (int g_ = 0; g_ < NB; ++g_) { __builtin_amdgcn_sched_group_barrier(0x008, 1, 0); __builtin_amdgcn_sched_group_barrier(0x100, 1, 0); __builtin_amdgcn_sched_group_barrier(0x400, 8 / NB, 0); __builtin_amdgcn_sched_group_barrier(0x002, 12 / NB, 0); } SBAR_();
;         VLOAD(2, va);
; #pragma unroll
;         for (int d0 = 0; d0 < 4; ++d0) { kf0[d0] = *(const LAS bf16x8*)(Kb + d0 * 32); kf1[d0] = *(const LAS bf16x8*)(Kb + 32 * KPB + d0 * 32); }
;         PVMMA(vb, pf1); EXPCVT(2, pf0, ps2); _Pragma("unroll") for (int g_ = 0; g_ < NB; ++g_) { __builtin_amdgcn_sched_group_barrier(0x008, 1, 0); __builtin_amdgcn_sched_group_barrier(0x100, 1, 0); __builtin_amdgcn_sched_group_barrier(0x400, 8 / NB, 0); __builtin_amdgcn_sched_group_barrier(0x002, 12 / NB, 0); } SBAR_();
;         {
;             f32x16 z0, z1;
; #pragma unroll
;             for (int r = 0; r < 16; ++r) { z0[r] = 0.f; z1[r] = 0.f; }
; #pragma unroll
.LBB0_510:
	s_add_i32 s10, s15, 3
	s_min_i32 s10, s10, s12
	s_min_i32 s8, s8, s12
	s_waitcnt vmcnt(0)
	v_mad_u64_u32 v[84:85], s[10:11], s10, v243, v[108:109]
	s_lshl_b64 s[10:11], s[8:9], 7
	s_nop 0
	v_lshl_add_u64 v[86:87], v[110:111], 0, s[10:11]
	global_load_dwordx4 v[88:91], v[84:85], off
	v_add_f32_e64 v16, -v149, v16
	global_load_dwordx4 v[84:87], v[86:87], off
	v_exp_f32_e32 v112, v16
	v_add_f32_e64 v16, -v149, v17
	v_exp_f32_e32 v114, v16
	v_add_f32_e64 v16, -v149, v18
	v_exp_f32_e32 v134, v16
	v_add_f32_e64 v16, -v149, v19
	v_exp_f32_e32 v138, v16
	v_add_f32_e64 v16, -v149, v20
	v_exp_f32_e32 v130, v16
	v_add_f32_e64 v16, -v149, v21
	s_bitcmp1_b32 s15, 0
	v_exp_f32_e32 v136, v16
	v_add_f32_e64 v16, -v149, v22
	s_cselect_b32 s8, 0x2400, 0
	v_exp_f32_e32 v128, v16
	v_add_f32_e64 v16, -v149, v23
	v_add_u32_e32 v150, s8, v147
	v_exp_f32_e32 v132, v16
	ds_read_b128 v[92:95], v150 offset:18432
	ds_read_b128 v[96:99], v150 offset:23040
	v_cvt_pk_bf16_f32 v16, v112, v114
	v_cvt_pk_bf16_f32 v17, v134, v138
	v_cvt_pk_bf16_f32 v18, v130, v136
	v_cvt_pk_bf16_f32 v19, v128, v132
	s_waitcnt lgkmcnt(1)
	s_nop 0
	v_mfma_f32_32x32x16_bf16 v[52:67], v[92:95], v[16:19], v[52:67]
	ds_read_b128 v[20:23], v150 offset:18464
	v_add_f32_e64 v24, -v149, v24
	v_exp_f32_e32 v126, v24
	v_add_f32_e64 v25, -v149, v25
	v_exp_f32_e32 v124, v25
	v_add_f32_e64 v26, -v149, v26
	v_exp_f32_e32 v142, v26
	v_add_f32_e64 v27, -v149, v27
	v_exp_f32_e32 v140, v27
	v_add_f32_e64 v28, -v149, v28
	v_cvt_pk_bf16_f32 v24, v126, v124
	s_waitcnt lgkmcnt(1)
	v_mfma_f32_32x32x16_bf16 v[36:51], v[96:99], v[16:19], v[36:51]
	ds_read_b128 v[16:19], v150 offset:23072
	v_exp_f32_e32 v118, v28
	v_add_f32_e64 v28, -v149, v29
	v_exp_f32_e32 v122, v28
	v_add_f32_e64 v28, -v149, v30
	v_exp_f32_e32 v116, v28
	v_add_f32_e64 v28, -v149, v31
	v_exp_f32_e32 v120, v28
	v_add_u32_e32 v28, s16, v145
	v_cvt_pk_bf16_f32 v25, v142, v140
	v_cvt_pk_bf16_f32 v26, v118, v122
	v_cvt_pk_bf16_f32 v27, v116, v120
	s_waitcnt lgkmcnt(1)
	s_nop 0
	v_mfma_f32_32x32x16_bf16 v[52:67], v[20:23], v[24:27], v[52:67]
	ds_read_b128 v[96:99], v150 offset:18496
	v_add_f32_e64 v0, -v149, v0
	v_exp_f32_e32 v113, v0
	v_add_f32_e64 v0, -v149, v7
	v_exp_f32_e32 v133, v0
	v_add_f32_e64 v1, -v149, v1
	v_exp_f32_e32 v115, v1
	v_add_f32_e64 v1, -v149, v6
	v_exp_f32_e32 v129, v1
	v_add_f32_e64 v2, -v149, v2
	v_exp_f32_e32 v135, v2
	v_add_f32_e64 v2, -v149, v5
	v_exp_f32_e32 v137, v2
	v_add_f32_e64 v3, -v149, v3
	v_exp_f32_e32 v139, v3
	v_add_f32_e64 v3, -v149, v4
	v_exp_f32_e32 v131, v3
	v_cvt_pk_bf16_f32 v107, v129, v133
	ds_read_b128 v[0:3], v28 offset:4608
	ds_read_b128 v[152:155], v28 offset:32
	v_cvt_pk_bf16_f32 v106, v131, v137
	s_waitcnt lgkmcnt(3)
	v_mfma_f32_32x32x16_bf16 v[36:51], v[16:19], v[24:27], v[36:51]
	ds_read_b128 v[16:19], v28
	ds_read_b128 v[20:23], v28 offset:4640
	ds_read_b128 v[156:159], v28 offset:64
	ds_read_b128 v[24:27], v28 offset:4672
	ds_read_b128 v[160:163], v28 offset:96
	ds_read_b128 v[28:31], v28 offset:4704
	ds_read_b128 v[92:95], v150 offset:23104
	v_cvt_pk_bf16_f32 v104, v113, v115
	v_cvt_pk_bf16_f32 v105, v135, v139
	v_add_f32_e64 v117, -v149, v14
	v_exp_f32_e32 v117, v117
	v_add_f32_e64 v4, -v149, v15
	v_add_f32_e64 v5, -v149, v9
	v_exp_f32_e32 v121, v4
	v_add_f32_e64 v4, -v149, v8
	v_add_f32_e64 v100, -v149, v11
	v_exp_f32_e32 v127, v4
	v_add_f32_e64 v4, -v149, v10
	v_add_f32_e64 v102, -v149, v12
	v_exp_f32_e32 v125, v5
	v_add_f32_e64 v103, -v149, v13
	v_exp_f32_e32 v143, v4
	s_waitcnt lgkmcnt(8)
	v_mfma_f32_32x32x16_bf16 v[0:15], v[0:3], v[68:71], 0
	s_waitcnt lgkmcnt(5)
	v_mfma_f32_32x32x16_bf16 v[0:15], v[20:23], v[72:75], v[0:15]
	s_waitcnt lgkmcnt(3)
	v_mfma_f32_32x32x16_bf16 v[0:15], v[24:27], v[76:79], v[0:15]
	s_waitcnt lgkmcnt(1)
	v_mfma_f32_32x32x16_bf16 v[0:15], v[28:31], v[80:83], v[0:15]
	v_mfma_f32_32x32x16_bf16 v[16:31], v[16:19], v[68:71], 0
	v_mfma_f32_32x32x16_bf16 v[16:31], v[152:155], v[72:75], v[16:31]
	v_mfma_f32_32x32x16_bf16 v[16:31], v[156:159], v[76:79], v[16:31]
	v_exp_f32_e32 v141, v100
	v_cvt_pk_bf16_f32 v100, v127, v125
	v_cvt_pk_bf16_f32 v101, v143, v141
	v_exp_f32_e32 v119, v102
	v_exp_f32_e32 v123, v103
	v_mfma_f32_32x32x16_bf16 v[16:31], v[160:163], v[80:83], v[16:31]
	v_cvt_pk_bf16_f32 v103, v117, v121
	v_cvt_pk_bf16_f32 v102, v119, v123
	ds_read_b128 v[152:155], v150 offset:18528
	ds_read_b128 v[156:159], v150 offset:23136
	v_mfma_f32_32x32x16_bf16 v[52:67], v[96:99], v[104:107], v[52:67]
	v_add_f32_e64 v96, v134, v138
	v_add_f32_e64 v97, v135, v139
	v_add_f32_e64 v98, v130, v136
	v_add_f32_e64 v99, v131, v137
	v_add_f32_e64 v128, v128, v132
	v_add_f32_e64 v129, v129, v133
	v_pk_add_f32 v[112:113], v[112:113], v[114:115]
	v_pk_add_f32 v[98:99], v[98:99], v[128:129]
	s_andn2_b64 vcc, exec, s[0:1]
	s_waitcnt lgkmcnt(2)
	v_mfma_f32_32x32x16_bf16 v[36:51], v[92:95], v[104:107], v[36:51]
	v_add_f32_e64 v92, v112, v96
	v_add_f32_e64 v93, v113, v97
	v_add_f32_e64 v96, v118, v122
	v_add_f32_e64 v97, v119, v123
	v_add_f32_e64 v92, v92, v98
	v_add_f32_e64 v93, v93, v99
	v_pk_add_f32 v[98:99], v[116:117], v[120:121]
	v_pk_add_f32 v[94:95], v[142:143], v[140:141]
	v_pk_add_f32 v[96:97], v[96:97], v[98:99]
	v_pk_add_f32 v[98:99], v[126:127], v[124:125]
	s_waitcnt lgkmcnt(1)
	v_mfma_f32_32x32x16_bf16 v[52:67], v[152:155], v[100:103], v[52:67]
	v_add_f32_e64 v94, v98, v94
	v_add_f32_e64 v95, v99, v95
	v_add_f32_e64 v94, v94, v96
	v_add_f32_e64 v95, v95, v97
	v_add_f32_e64 v92, v92, v94
	v_add_f32_e64 v93, v93, v95
	v_add_f32_e32 v92, v92, v93
	s_waitcnt lgkmcnt(0)
	v_mfma_f32_32x32x16_bf16 v[36:51], v[156:159], v[100:103], v[36:51]
	v_add_f32_e32 v146, v146, v92
	s_cbranch_vccnz .LBB0_513
	ds_read2_b32 v[112:113], v148 offset1:1
	ds_read2_b32 v[114:115], v148 offset0:2 offset1:3
	ds_read2_b32 v[116:117], v148 offset0:8 offset1:9
	ds_read2_b32 v[118:119], v148 offset0:10 offset1:11
	ds_read2_b32 v[120:121], v148 offset0:16 offset1:17
	ds_read2_b32 v[122:123], v148 offset0:18 offset1:19
	ds_read2_b32 v[124:125], v148 offset0:24 offset1:25
	ds_read2_b32 v[126:127], v148 offset0:26 offset1:27
	ds_read2_b32 v[128:129], v148 offset0:32 offset1:33
	ds_read2_b32 v[130:131], v148 offset0:34 offset1:35
	ds_read2_b32 v[132:133], v148 offset0:40 offset1:41
	ds_read2_b32 v[134:135], v148 offset0:42 offset1:43
	ds_read2_b32 v[136:137], v148 offset0:48 offset1:49
	ds_read2_b32 v[138:139], v148 offset0:50 offset1:51
	ds_read2_b32 v[140:141], v148 offset0:56 offset1:57
	s_waitcnt lgkmcnt(14)
	ds_read2_b32 v[142:143], v148 offset0:58 offset1:59
	v_pk_add_f32 v[16:17], v[16:17], v[112:113]
	s_waitcnt lgkmcnt(14)
	v_pk_add_f32 v[18:19], v[18:19], v[114:115]
	s_waitcnt lgkmcnt(13)
	v_pk_add_f32 v[20:21], v[20:21], v[116:117]
	s_waitcnt lgkmcnt(12)
	v_pk_add_f32 v[22:23], v[22:23], v[118:119]
	s_waitcnt lgkmcnt(11)
	v_pk_add_f32 v[24:25], v[24:25], v[120:121]
	s_waitcnt lgkmcnt(10)
	v_pk_add_f32 v[26:27], v[26:27], v[122:123]
	s_waitcnt lgkmcnt(9)
	v_pk_add_f32 v[28:29], v[28:29], v[124:125]
	s_waitcnt lgkmcnt(8)
	v_pk_add_f32 v[30:31], v[30:31], v[126:127]
	s_waitcnt lgkmcnt(7)
	v_pk_add_f32 v[0:1], v[0:1], v[128:129]
	s_waitcnt lgkmcnt(6)
	v_pk_add_f32 v[2:3], v[2:3], v[130:131]
	s_waitcnt lgkmcnt(5)
	v_pk_add_f32 v[4:5], v[4:5], v[132:133]
	s_waitcnt lgkmcnt(4)
	v_pk_add_f32 v[6:7], v[6:7], v[134:135]
	s_waitcnt lgkmcnt(3)
	v_pk_add_f32 v[8:9], v[8:9], v[136:137]
	s_waitcnt lgkmcnt(2)
	v_pk_add_f32 v[10:11], v[10:11], v[138:139]
	s_waitcnt lgkmcnt(1)
	v_pk_add_f32 v[12:13], v[12:13], v[140:141]
	s_waitcnt lgkmcnt(0)
	v_pk_add_f32 v[14:15], v[14:15], v[142:143]
	v_max_f32_e32 v92, v16, v0
	v_max3_f32 v93, v1, v18, v2
	v_max3_f32 v92, v92, v17, v19
	v_max3_f32 v93, v93, v20, v4
	v_max3_f32 v92, v92, v3, v21
	v_max3_f32 v93, v93, v22, v6
	v_max3_f32 v92, v92, v5, v23
	v_max3_f32 v93, v93, v24, v8
	v_max3_f32 v92, v92, v7, v25
	v_max3_f32 v93, v93, v26, v10
	v_max3_f32 v92, v92, v9, v27
	v_max3_f32 v93, v93, v28, v12
	v_max3_f32 v92, v92, v11, v29
	v_max3_f32 v93, v93, v30, v14
	v_max3_f32 v92, v92, v13, v31
	v_max3_f32 v92, v92, v15, v93
	v_mov_b32_e32 v93, v92
	s_nop 1
	v_permlane32_swap_b32_e32 v92, v93
	v_max_f32_e32 v93, v93, v93
	v_max_f32_e32 v92, v92, v92
	v_max_f32_e32 v92, v92, v93
	v_cmp_gt_f32_e32 vcc, v92, v149
	s_cbranch_vccz .LBB0_513
	v_add_f32_e32 v92, 0, v92
	v_max_f32_e32 v93, v149, v149
	v_max_f32_e32 v93, v93, v92
	v_sub_f32_e32 v92, v149, v93
	v_exp_f32_e32 v92, v92
	v_mov_b32_e32 v149, v93
	v_pk_mul_f32 v[50:51], v[50:51], v[92:93] op_sel_hi:[1,0]
	v_pk_mul_f32 v[48:49], v[48:49], v[92:93] op_sel_hi:[1,0]
	v_pk_mul_f32 v[46:47], v[46:47], v[92:93] op_sel_hi:[1,0]
	v_pk_mul_f32 v[44:45], v[44:45], v[92:93] op_sel_hi:[1,0]
	v_pk_mul_f32 v[42:43], v[42:43], v[92:93] op_sel_hi:[1,0]
	v_pk_mul_f32 v[40:41], v[40:41], v[92:93] op_sel_hi:[1,0]
	v_pk_mul_f32 v[38:39], v[38:39], v[92:93] op_sel_hi:[1,0]
	v_pk_mul_f32 v[36:37], v[36:37], v[92:93] op_sel_hi:[1,0]
	v_pk_mul_f32 v[66:67], v[66:67], v[92:93] op_sel_hi:[1,0]
	v_pk_mul_f32 v[64:65], v[64:65], v[92:93] op_sel_hi:[1,0]
	v_pk_mul_f32 v[62:63], v[62:63], v[92:93] op_sel_hi:[1,0]
	v_pk_mul_f32 v[60:61], v[60:61], v[92:93] op_sel_hi:[1,0]
	v_pk_mul_f32 v[58:59], v[58:59], v[92:93] op_sel_hi:[1,0]
	v_pk_mul_f32 v[56:57], v[56:57], v[92:93] op_sel_hi:[1,0]
	v_pk_mul_f32 v[54:55], v[54:55], v[92:93] op_sel_hi:[1,0]
	v_pk_mul_f32 v[52:53], v[52:53], v[92:93] op_sel_hi:[1,0]
	v_mul_f32_e32 v146, v146, v92
